# weight-conversion loop (W_up/W_down share): the previous item's stores stay in flight across the head wait (no exposed store acknowledgement per item)
# baseline (speedup 1.0000x reference)
.LBB0_422:
	v_bfe_u32 v66, v34, 3, 3
	v_lshlrev_b32_e32 v0, 2, v34
	v_and_b32_e32 v36, 28, v0
	v_or_b32_e32 v68, 8, v66
	v_or_b32_e32 v70, 16, v66
	v_or_b32_e32 v72, 24, v66
	v_or_b32_e32 v67, 32, v66
	v_or_b32_e32 v69, 40, v66
	v_or_b32_e32 v71, 48, v66
	v_or_b32_e32 v73, 56, v66
	v_lshlrev_b32_e32 v0, 2, v36
	s_waitcnt vmcnt(0)
	v_mul_u32_u24_e32 v2, s28, v66
	v_mul_u32_u24_e32 v4, s28, v68
	s_waitcnt vmcnt(0)
	v_mul_u32_u24_e32 v10, s28, v70
	v_mul_u32_u24_e32 v12, s28, v72
	v_mul_u32_u24_e32 v18, s28, v67
	v_mul_u32_u24_e32 v20, s28, v69
	v_mul_u32_u24_e32 v28, s28, v71
	v_mul_u32_u24_e32 v30, s28, v73
	v_lshl_add_u64 v[26:27], s[26:27], 0, v[0:1]
	v_lshlrev_b32_e32 v2, 2, v2
	v_mov_b32_e32 v3, v1
	v_lshlrev_b32_e32 v4, 2, v4
	v_mov_b32_e32 v5, v1
	v_lshlrev_b32_e32 v10, 2, v10
	v_mov_b32_e32 v11, v1
	v_lshlrev_b32_e32 v12, 2, v12
	v_mov_b32_e32 v13, v1
	v_lshlrev_b32_e32 v18, 2, v18
	v_mov_b32_e32 v19, v1
	v_lshlrev_b32_e32 v20, 2, v20
	v_mov_b32_e32 v21, v1
	v_lshlrev_b32_e32 v28, 2, v28
	v_mov_b32_e32 v29, v1
	v_lshlrev_b32_e32 v30, 2, v30
	v_mov_b32_e32 v31, v1
	v_lshl_add_u64 v[2:3], v[26:27], 0, v[2:3]
	v_lshl_add_u64 v[6:7], v[26:27], 0, v[4:5]
	v_lshl_add_u64 v[10:11], v[26:27], 0, v[10:11]
	v_lshl_add_u64 v[14:15], v[26:27], 0, v[12:13]
	v_lshl_add_u64 v[18:19], v[26:27], 0, v[18:19]
	v_lshl_add_u64 v[22:23], v[26:27], 0, v[20:21]
	v_lshl_add_u64 v[28:29], v[26:27], 0, v[28:29]
	v_lshl_add_u64 v[30:31], v[26:27], 0, v[30:31]
	global_load_dwordx4 v[2:5], v[2:3], off
	s_nop 0
	global_load_dwordx4 v[6:9], v[6:7], off
	s_nop 0
	global_load_dwordx4 v[10:13], v[10:11], off
	s_nop 0
	global_load_dwordx4 v[14:17], v[14:15], off
	s_nop 0
	global_load_dwordx4 v[18:21], v[18:19], off
	s_nop 0
	global_load_dwordx4 v[22:25], v[22:23], off
	s_nop 0
	global_load_dwordx4 v[26:29], v[28:29], off
	s_nop 0
	global_load_dwordx4 v[30:33], v[30:31], off
	s_mulk_i32 s19, 0x3000
	s_add_i32 s30, s19, 0
	s_mul_i32 s4, s3, 0xb00000
	s_mul_hi_u32 s19, s2, 0xb00000
	s_add_i32 s19, s19, s4
	s_mul_i32 s4, s3, 0x580000
	s_mul_hi_u32 s26, s2, 0x580000
	s_add_i32 s17, s14, 0xffffff00
	v_readlane_b32 s49, v255, 60
	s_cmp_eq_u32 s49, 0
	s_cselect_b32 s17, s17, 0x300
	s_add_i32 s26, s26, s4
	s_mul_i32 s4, s2, 0x580000
	s_add_u32 s4, s20, s4
	s_addc_u32 s26, s21, s26
	s_add_u32 s39, s4, 0x4200000
	s_addc_u32 s40, s26, 0
	s_mul_i32 s4, s3, 0x1600000
	s_mul_hi_u32 s26, s2, 0x1600000
	s_mul_i32 s38, s2, 0xb00000
	s_add_i32 s41, s26, s4
	s_add_u32 s4, s36, s38
	s_addc_u32 s5, s5, s19
	s_lshl_b64 s[26:27], s[2:3], 20
	s_lshl_b64 s[28:29], s[2:3], 21
	s_add_u32 s28, s20, s28
	s_addc_u32 s29, s21, s29
	s_add_u32 s43, s28, 0xe00000
	s_addc_u32 s44, s29, 0
	s_mul_i32 s28, s3, 0x500000
	s_mul_hi_u32 s29, s2, 0x500000
	s_add_i32 s45, s29, s28
	s_mul_i32 s3, s3, 0x280000
	s_mul_hi_u32 s28, s2, 0x280000
	s_mul_i32 s42, s2, 0x1600000
	s_mul_i32 s46, s2, 0x500000
	s_add_i32 s28, s28, s3
	s_mul_i32 s2, s2, 0x280000
	s_add_u32 s2, s20, s2
	s_addc_u32 s3, s21, s28
	v_add_u32_e32 v35, s30, v0
	v_lshlrev_b32_e32 v0, 3, v34
	s_add_u32 s47, s2, 0x200000
	v_and_b32_e32 v34, 56, v0
	s_addc_u32 s48, s3, 0
	v_mul_u32_u24_e32 v37, 0x84, v66
	v_mul_u32_u24_e32 v0, 0x84, v34
	v_lshlrev_b32_e32 v38, 2, v66
	s_add_i32 s49, s34, s17
	v_add3_u32 v76, s30, v0, v38
	s_lshl_b32 s50, s49, 5
	s_lshl_b32 s51, s17, 5
	s_lshl_b32 s52, s49, 7
	s_lshl_b32 s53, s17, 7
	s_lshl_b32 s56, s49, 1
	s_lshl_b32 s57, s17, 1
	s_lshl_b64 s[26:27], s[26:27], 2
	v_lshlrev_b32_e32 v0, 2, v36
	v_add_u32_e32 v77, v35, v37
	v_lshlrev_b32_e32 v74, 1, v34
	s_mov_b64 s[2:3], s[6:7]
	s_mov_b32 s54, s13
	v_mov_b32_e32 v34, 0x3f00
	global_store_dword v34, v1, s[20:21]
	global_store_dword v34, v1, s[20:21]
	global_store_dword v34, v1, s[20:21]
	global_store_dword v34, v1, s[20:21]
	s_branch .LBB0_424

.LBB0_436:
	v_mul_u32_u24_e32 v34, s34, v66
	v_mul_u32_u24_e32 v36, s34, v68
	v_mul_u32_u24_e32 v42, s34, v70
	v_mul_u32_u24_e32 v44, s34, v72
	v_mul_u32_u24_e32 v50, s34, v67
	v_mul_u32_u24_e32 v52, s34, v69
	v_mul_u32_u24_e32 v60, s34, v71
	v_mul_u32_u24_e32 v62, s34, v73
	v_lshl_add_u64 v[58:59], s[30:31], 0, v[0:1]
	v_lshlrev_b32_e32 v34, 2, v34
	v_mov_b32_e32 v35, v1
	v_lshlrev_b32_e32 v36, 2, v36
	v_mov_b32_e32 v37, v1
	v_lshlrev_b32_e32 v42, 2, v42
	v_mov_b32_e32 v43, v1
	v_lshlrev_b32_e32 v44, 2, v44
	v_mov_b32_e32 v45, v1
	v_lshlrev_b32_e32 v50, 2, v50
	v_mov_b32_e32 v51, v1
	v_lshlrev_b32_e32 v52, 2, v52
	v_mov_b32_e32 v53, v1
	v_lshlrev_b32_e32 v60, 2, v60
	v_mov_b32_e32 v61, v1
	v_lshlrev_b32_e32 v62, 2, v62
	v_mov_b32_e32 v63, v1
	v_lshl_add_u64 v[34:35], v[58:59], 0, v[34:35]
	v_lshl_add_u64 v[36:37], v[58:59], 0, v[36:37]
	v_lshl_add_u64 v[42:43], v[58:59], 0, v[42:43]
	v_lshl_add_u64 v[44:45], v[58:59], 0, v[44:45]
	v_lshl_add_u64 v[50:51], v[58:59], 0, v[50:51]
	v_lshl_add_u64 v[52:53], v[58:59], 0, v[52:53]
	v_lshl_add_u64 v[60:61], v[58:59], 0, v[60:61]
	v_lshl_add_u64 v[58:59], v[58:59], 0, v[62:63]
	global_load_dwordx4 v[38:41], v[34:35], off
	s_nop 0
	global_load_dwordx4 v[34:37], v[36:37], off
	s_nop 0
	global_load_dwordx4 v[46:49], v[42:43], off
	s_nop 0
	global_load_dwordx4 v[42:45], v[44:45], off
	s_nop 0
	global_load_dwordx4 v[54:57], v[50:51], off
	s_nop 0
	global_load_dwordx4 v[50:53], v[52:53], off
	s_nop 0
	global_load_dwordx4 v[62:65], v[60:61], off
	s_nop 0
	global_load_dwordx4 v[58:61], v[58:59], off
	s_waitcnt vmcnt(12)
	s_branch .Lcv1_go
.Lcv1_last:
	s_waitcnt vmcnt(4)
.LBB0_437:
.Lcv1_go:
	ds_write2_b32 v77, v2, v3 offset1:1
	ds_write2_b32 v77, v4, v5 offset0:2 offset1:3
	v_add_u32_e32 v2, 0x420, v77
	ds_write2_b32 v2, v6, v7 offset1:1
	v_add_u32_e32 v2, 0x428, v77
	ds_write2_b32 v2, v8, v9 offset1:1
	v_add_u32_e32 v2, 0x840, v77
	ds_write2_b32 v2, v10, v11 offset1:1
	v_add_u32_e32 v2, 0x848, v77
	ds_write2_b32 v2, v12, v13 offset1:1
	v_add_u32_e32 v2, 0xc60, v77
	ds_write2_b32 v2, v14, v15 offset1:1
	v_add_u32_e32 v2, 0xc68, v77
	ds_write2_b32 v2, v16, v17 offset1:1
	v_add_u32_e32 v2, 0x1080, v77
	ds_write2_b32 v2, v18, v19 offset1:1
	v_add_u32_e32 v2, 0x1088, v77
	ds_write2_b32 v2, v20, v21 offset1:1
	v_add_u32_e32 v2, 0x14a0, v77
	ds_write2_b32 v2, v22, v23 offset1:1
	v_add_u32_e32 v2, 0x14a8, v77
	ds_write2_b32 v2, v24, v25 offset1:1
	v_add_u32_e32 v2, 0x18c0, v77
	ds_write2_b32 v2, v26, v27 offset1:1
	v_add_u32_e32 v2, 0x18c8, v77
	ds_write2_b32 v2, v28, v29 offset1:1
	v_add_u32_e32 v2, 0x1ce0, v77
	ds_write2_b32 v2, v30, v31 offset1:1
	v_add_u32_e32 v2, 0x1ce8, v77
	ds_write2_b32 v2, v32, v33 offset1:1
	s_waitcnt lgkmcnt(0)
	ds_read2_b32 v[2:3], v76 offset1:33
	s_waitcnt lgkmcnt(0)
	v_cvt_pk_bf16_f32 v2, v2, v3
	ds_read2_b32 v[4:5], v76 offset0:66 offset1:99
	v_mov_b32_e32 v75, v1
	s_waitcnt lgkmcnt(0)
	v_cvt_pk_bf16_f32 v3, v4, v5
	ds_read2_b32 v[4:5], v76 offset0:132 offset1:165
	v_lshl_add_u64 v[8:9], s[6:7], 0, v[74:75]
	v_mad_u64_u32 v[10:11], s[6:7], s13, v66, 0
	s_waitcnt lgkmcnt(0)
	v_cvt_pk_bf16_f32 v4, v4, v5
	ds_read2_b32 v[6:7], v76 offset0:198 offset1:231
	s_waitcnt lgkmcnt(0)
	v_cvt_pk_bf16_f32 v5, v6, v7
	v_lshl_add_u64 v[10:11], v[10:11], 1, v[8:9]
	ds_read2_b32 v[6:7], v76 offset0:8 offset1:41
	global_store_dwordx4 v[10:11], v[2:5], off
	v_mad_u64_u32 v[10:11], s[6:7], s13, v68, 0
	s_waitcnt lgkmcnt(0)
	v_cvt_pk_bf16_f32 v2, v6, v7
	ds_read2_b32 v[4:5], v76 offset0:74 offset1:107
	s_waitcnt lgkmcnt(0)
	v_cvt_pk_bf16_f32 v3, v4, v5
	ds_read2_b32 v[4:5], v76 offset0:140 offset1:173
	s_waitcnt lgkmcnt(0)
	v_cvt_pk_bf16_f32 v4, v4, v5
	ds_read2_b32 v[6:7], v76 offset0:206 offset1:239
	s_waitcnt lgkmcnt(0)
	v_cvt_pk_bf16_f32 v5, v6, v7
	v_lshl_add_u64 v[10:11], v[10:11], 1, v[8:9]
	ds_read2_b32 v[6:7], v76 offset0:16 offset1:49
	global_store_dwordx4 v[10:11], v[2:5], off
	v_mad_u64_u32 v[10:11], s[6:7], s13, v70, 0
	s_waitcnt lgkmcnt(0)
	v_cvt_pk_bf16_f32 v2, v6, v7
	ds_read2_b32 v[4:5], v76 offset0:82 offset1:115
	s_waitcnt lgkmcnt(0)
	v_cvt_pk_bf16_f32 v3, v4, v5
	ds_read2_b32 v[4:5], v76 offset0:148 offset1:181
	s_waitcnt lgkmcnt(0)
	v_cvt_pk_bf16_f32 v4, v4, v5
	ds_read2_b32 v[6:7], v76 offset0:214 offset1:247
	s_waitcnt lgkmcnt(0)
	v_cvt_pk_bf16_f32 v5, v6, v7
	v_lshl_add_u64 v[10:11], v[10:11], 1, v[8:9]
	ds_read2_b32 v[6:7], v76 offset0:24 offset1:57
	global_store_dwordx4 v[10:11], v[2:5], off
	v_mad_u64_u32 v[10:11], s[6:7], s13, v72, 0
	s_waitcnt lgkmcnt(0)
	v_cvt_pk_bf16_f32 v2, v6, v7
	ds_read2_b32 v[4:5], v76 offset0:90 offset1:123
	s_waitcnt lgkmcnt(0)
	v_cvt_pk_bf16_f32 v3, v4, v5
	ds_read2_b32 v[4:5], v76 offset0:156 offset1:189
	v_lshl_add_u64 v[8:9], v[10:11], 1, v[8:9]
	s_waitcnt lgkmcnt(0)
	v_cvt_pk_bf16_f32 v4, v4, v5
	ds_read2_b32 v[6:7], v76 offset0:222 offset1:255
	s_waitcnt lgkmcnt(0)
	v_cvt_pk_bf16_f32 v5, v6, v7
	global_store_dwordx4 v[8:9], v[2:5], off
	s_waitcnt lgkmcnt(0)
	s_andn2_b64 vcc, exec, s[28:29]
	s_mov_b64 s[6:7], -1
	s_cbranch_vccnz .LBB0_423
	s_add_i32 s49, s49, s17
	s_add_i32 s50, s50, s51
	s_add_i32 s52, s52, s53
	s_add_i32 s56, s56, s57
	s_mov_b64 s[6:7], 0
	s_branch .LBB0_423
